# DSA batch tail: transposed V reads and P fragment read issued before the alpha broadcast wait
# baseline (speedup 1.0000x reference)
; #define LAS __attribute__((address_space(3)))
; __device__ __forceinline__ u16 f2bf(float f) { return (u16)(cvtpk(f, 0.f) & 0xffffu); }
;     ...
;               ss += __shfl_xor(ss, 16); ss += __shfl_xor(ss, 32);
;               const float rstd = rsqrtf(ss * (1.f / 128.f) + EPS);
;               const float av = quad == 0 ? a[0] : (quad == 1 ? a[1] : (quad == 2 ? a[2] : a[3]));
;               rsv[jj] = rstd; lgv[jj] = (slot < kcount) ? av * rstd * 0.08838834764831845f : -__builtin_inff();
;           }
;           if (b + 1 < nb) gl(b + 1);
;           float mx = fmaxf(fmaxf(lgv[0], lgv[1]), fmaxf(lgv[2], lgv[3]));
; #pragma unroll
;           for (int o = 1; o < 16; o <<= 1) mx = fmaxf(mx, __shfl_xor(mx, o));
;           const float mnew = fmaxf(mrun, mx), alpha = __expf(mrun - mnew); mrun = mnew;
;           float ps = 0.f;
; #pragma unroll
;           for (int jj = 0; jj < 4; ++jj) { const float pe = __expf(lgv[jj] - mnew); ps += pe; pbT[quad * 64 + jj * 16 + c16] = f2bf(pe * rsv[jj]); }
;           lsum = lsum * alpha + ps;
;           if (c16 == 0) alf[quad] = alpha;
;           const f32x4 al4 = *(const LAS f32x4*)alf;
; #pragma unroll
;           for (int c = 0; c < 8; ++c) oacc[c] *= al4;
; #pragma unroll
;           for (int ks = 0; ks < 2; ++ks) {
;               const bf16x8 pf = *(const LAS bf16x8*)(pbT + (c16 & 3) * 64 + ks * 32 + quad * 8);
;               u16x4 t0[8], t1[8];
;     ...
;               if (ks == 0) { TRR8(t0, 0, 0); TRR8(t1, 1, 0); } else { TRR8(t0, 0, 8192); TRR8(t1, 1, 8192); }
.LBB0_946:
	s_waitcnt lgkmcnt(1)
	v_add_f32_e32 v119, v119, v175
	v_fmamk_f32 v119, v119, 0x3c000000, v199
	v_cmp_gt_f32_e32 vcc, s85, v119
	v_mul_f32_e32 v121, 0x4b800000, v119
	v_add_u32_e32 v0, 48, v157
	v_cndmask_b32_e32 v119, v119, v121, vcc
	v_rsq_f32_e32 v119, v119
	v_add_f32_e32 v117, v117, v174
	v_fmamk_f32 v117, v117, 0x3c000000, v199
	v_add_f32_e32 v115, v115, v173
	v_mul_f32_e32 v121, 0x45800000, v119
	v_cndmask_b32_e32 v122, v119, v121, vcc
	v_cmp_gt_i32_e32 vcc, s22, v0
	v_mul_f32_e32 v0, v122, v120
	v_mul_f32_e32 v0, 0x3db504f3, v0
	v_cndmask_b32_e32 v121, v208, v0, vcc
	v_cmp_gt_f32_e32 vcc, s85, v117
	v_mul_f32_e32 v119, 0x4b800000, v117
	v_add_u32_e32 v0, 32, v157
	v_cndmask_b32_e32 v117, v117, v119, vcc
	v_rsq_f32_e32 v117, v117
	v_fmamk_f32 v115, v115, 0x3c000000, v199
	v_mul_f32_e32 v119, 0x45800000, v117
	v_cndmask_b32_e32 v123, v117, v119, vcc
	v_cmp_gt_i32_e32 vcc, s22, v0
	v_mul_f32_e32 v0, v123, v118
	v_mul_f32_e32 v0, 0x3db504f3, v0
	v_cndmask_b32_e32 v120, v208, v0, vcc
	v_cmp_gt_f32_e32 vcc, s85, v115
	v_mul_f32_e32 v117, 0x4b800000, v115
	v_add_u32_e32 v0, 16, v157
	v_cndmask_b32_e32 v115, v115, v117, vcc
	v_rsq_f32_e32 v115, v115
	s_nop 0
	v_mul_f32_e32 v117, 0x45800000, v115
	v_cndmask_b32_e32 v125, v115, v117, vcc
	v_cmp_gt_i32_e32 vcc, s22, v0
	v_mul_f32_e32 v0, v125, v116
	v_mul_f32_e32 v0, 0x3db504f3, v0
	v_cndmask_b32_e32 v119, v208, v0, vcc
	v_add_f32_e32 v0, v161, v172
	v_fmamk_f32 v0, v0, 0x3c000000, v199
	v_cmp_gt_f32_e32 vcc, s85, v0
	v_mul_f32_e32 v115, 0x4b800000, v0
	s_nop 0
	v_cndmask_b32_e32 v0, v0, v115, vcc
	v_rsq_f32_e32 v0, v0
	s_nop 0
	v_mul_f32_e32 v115, 0x45800000, v0
	v_cndmask_b32_e32 v161, v0, v115, vcc
	v_mul_f32_e32 v0, v161, v114
	v_cmp_gt_i32_e32 vcc, s22, v157
	v_mul_f32_e32 v0, 0x3db504f3, v0
	s_nop 0
	v_cndmask_b32_e32 v118, v208, v0, vcc
	v_max_f32_e32 v0, v120, v121
	v_max3_f32 v114, v118, v119, v0
	s_nop 1
	v_max_f32_dpp v115, v114, v114 quad_perm:[1,0,3,2] row_mask:0xf bank_mask:0xf
	s_nop 1
	v_max_f32_dpp v116, v115, v115 quad_perm:[2,3,0,1] row_mask:0xf bank_mask:0xf
	s_nop 1
	v_max_f32_dpp v117, v116, v116 row_ror:4 row_mask:0xf bank_mask:0xf
	s_nop 1
	v_max_f32_dpp v172, v117, v117 row_ror:8 row_mask:0xf bank_mask:0xf
	v_xor_b32_e32 v0, 1, v206
	v_xor_b32_e32 v114, 2, v206
	v_xor_b32_e32 v115, 4, v206
	v_xor_b32_e32 v116, 8, v206
	v_max3_f32 v117, v160, v117, v172
	v_sub_f32_e32 v118, v118, v117
	v_sub_f32_e32 v119, v119, v117
	v_sub_f32_e32 v120, v120, v117
	v_sub_f32_e32 v121, v121, v117
	v_mul_f32_e32 v118, 0x3fb8aa3b, v118
	v_mul_f32_e32 v119, 0x3fb8aa3b, v119
	v_mul_f32_e32 v120, 0x3fb8aa3b, v120
	v_mul_f32_e32 v121, 0x3fb8aa3b, v121
	v_exp_f32_e32 v118, v118
	v_exp_f32_e32 v119, v119
	v_exp_f32_e32 v120, v120
	v_exp_f32_e32 v121, v121
	v_sub_f32_e32 v160, v160, v117
	v_mul_f32_e32 v161, v161, v118
	v_mul_f32_e32 v125, v125, v119
	v_mul_f32_e32 v123, v123, v120
	v_mul_f32_e32 v122, v122, v121
	v_mul_f32_e32 v160, 0x3fb8aa3b, v160
	v_cvt_pk_bf16_f32 v161, v161, v1
	ds_write_b16 v155, v161 offset:1024
	v_cvt_pk_bf16_f32 v125, v125, v1
	ds_write_b16 v155, v125 offset:1056
	v_cvt_pk_bf16_f32 v123, v123, v1
	ds_write_b16 v155, v123 offset:1088
	v_cvt_pk_bf16_f32 v122, v122, v1
	ds_write_b16 v155, v122 offset:1120
	v_exp_f32_e32 v122, v160
	s_and_saveexec_b64 s[0:1], s[38:39]
	ds_write_b32 v129, v122 offset:640
	s_or_b64 exec, exec, s[0:1]
	v_add_f32_e32 v118, 0, v118
	v_add_f32_e32 v118, v119, v118
	v_add_f32_e32 v118, v120, v118
	v_add_f32_e32 v118, v121, v118
	v_mov_b32_e32 v119, s56
	v_fmac_f32_e32 v118, v159, v122
	ds_read_b128 v[120:123], v119 offset:640
	v_add_u32_e32 v154, 0x80, v154
	v_add_u32_e32 v157, 64, v157
	s_cmp_eq_u32 s23, s24
	ds_read_b128 v[244:247], v156 offset:1024
	ds_read_b64_tr_b16 v[216:217], v130 offset:0
	ds_read_b64_tr_b16 v[218:219], v138 offset:0
	ds_read_b64_tr_b16 v[212:213], v131 offset:0
	ds_read_b64_tr_b16 v[214:215], v139 offset:0
	ds_read_b64_tr_b16 v[194:195], v132 offset:0
	ds_read_b64_tr_b16 v[196:197], v140 offset:0
	ds_read_b64_tr_b16 v[190:191], v133 offset:0
	ds_read_b64_tr_b16 v[192:193], v141 offset:0
	ds_read_b64_tr_b16 v[186:187], v134 offset:0
	ds_read_b64_tr_b16 v[188:189], v142 offset:0
	s_waitcnt lgkmcnt(11)
; #define LAS __attribute__((address_space(3)))
;     ...
;           const f32x4 al4 = *(const LAS f32x4*)alf;
; #pragma unroll
;           for (int c = 0; c < 8; ++c) oacc[c] *= al4;
; #pragma unroll
;           for (int ks = 0; ks < 2; ++ks) {
;               const bf16x8 pf = *(const LAS bf16x8*)(pbT + (c16 & 3) * 64 + ks * 32 + quad * 8);
;               u16x4 t0[8], t1[8];
;     ...
;               if (ks == 0) { TRR8(t0, 0, 0); TRR8(t1, 1, 0); } else { TRR8(t0, 0, 8192); TRR8(t1, 1, 8192); }
;     ...
; #pragma unroll
;               for (int c = 0; c < 8; ++c) {
;                   const bf16x8 bf = {(short)t0[c][0], (short)t0[c][1], (short)t0[c][2], (short)t0[c][3], (short)t1[c][0], (short)t1[c][1], (short)t1[c][2], (short)t1[c][3]};
;                   oacc[c] = __builtin_amdgcn_mfma_f32_16x16x32_bf16(pf, bf, oacc[c], 0, 0, 0);
;               }
;           }
	v_pk_mul_f32 v[174:175], v[92:93], v[122:123]
	v_pk_mul_f32 v[172:173], v[90:91], v[120:121]
	v_pk_mul_f32 v[92:93], v[96:97], v[122:123]
	v_pk_mul_f32 v[90:91], v[94:95], v[120:121]
	v_pk_mul_f32 v[106:107], v[106:107], v[120:121]
	v_pk_mul_f32 v[110:111], v[110:111], v[120:121]
	v_pk_mul_f32 v[176:177], v[82:83], v[120:121]
	v_pk_mul_f32 v[182:183], v[86:87], v[120:121]
	v_pk_mul_f32 v[86:87], v[102:103], v[120:121]
	v_pk_mul_f32 v[82:83], v[98:99], v[120:121]
	v_pk_mul_f32 v[108:109], v[108:109], v[122:123]
	v_pk_mul_f32 v[112:113], v[112:113], v[122:123]
	v_pk_mul_f32 v[178:179], v[84:85], v[122:123]
	v_pk_mul_f32 v[184:185], v[88:89], v[122:123]
	v_pk_mul_f32 v[88:89], v[104:105], v[122:123]
	v_pk_mul_f32 v[84:85], v[100:101], v[122:123]
	ds_read_b64_tr_b16 v[120:121], v135 offset:0
	ds_read_b64_tr_b16 v[122:123], v143 offset:0
	ds_read_b64_tr_b16 v[102:103], v136 offset:0
	ds_read_b64_tr_b16 v[104:105], v144 offset:0
	s_waitcnt lgkmcnt(12)
	v_mfma_f32_16x16x32_bf16 v[106:109], v[244:247], v[216:219], v[106:109]
	ds_read_b64_tr_b16 v[98:99], v137 offset:0
	ds_read_b64_tr_b16 v[100:101], v145 offset:0
	s_waitcnt lgkmcnt(12)
	v_mfma_f32_16x16x32_bf16 v[110:113], v[244:247], v[212:215], v[110:113]
	s_waitcnt lgkmcnt(10)
	v_mfma_f32_16x16x32_bf16 v[172:175], v[244:247], v[194:197], v[172:175]
	s_waitcnt lgkmcnt(8)
	v_mfma_f32_16x16x32_bf16 v[176:179], v[244:247], v[190:193], v[176:179]
	s_waitcnt lgkmcnt(6)
	v_mfma_f32_16x16x32_bf16 v[182:185], v[244:247], v[186:189], v[182:185]
	s_waitcnt lgkmcnt(4)
	v_mfma_f32_16x16x32_bf16 v[120:123], v[244:247], v[120:123], v[90:93]
	s_waitcnt lgkmcnt(2)
	v_mfma_f32_16x16x32_bf16 v[102:105], v[244:247], v[102:105], v[86:89]
	s_waitcnt lgkmcnt(0)
	v_mfma_f32_16x16x32_bf16 v[98:101], v[244:247], v[98:101], v[82:85]
	ds_read_b128 v[220:223], v156 offset:1088
	ds_read_b64_tr_b16 v[212:213], v130 offset:8192
	ds_read_b64_tr_b16 v[214:215], v138 offset:8192
	ds_read_b64_tr_b16 v[194:195], v131 offset:8192
	ds_read_b64_tr_b16 v[196:197], v139 offset:8192
	ds_read_b64_tr_b16 v[90:91], v132 offset:8192
	ds_read_b64_tr_b16 v[92:93], v140 offset:8192
	ds_read_b64_tr_b16 v[82:83], v133 offset:8192
	ds_read_b64_tr_b16 v[84:85], v141 offset:8192
	ds_read_b64_tr_b16 v[86:87], v134 offset:8192
	ds_read_b64_tr_b16 v[88:89], v142 offset:8192
	ds_read_b64_tr_b16 v[94:95], v135 offset:8192
	ds_read_b64_tr_b16 v[96:97], v143 offset:8192
	ds_read_b64_tr_b16 v[190:191], v136 offset:8192
	ds_read_b64_tr_b16 v[192:193], v144 offset:8192
	s_waitcnt lgkmcnt(12)
	v_mfma_f32_16x16x32_bf16 v[106:109], v[220:223], v[212:215], v[106:109]
	ds_read_b64_tr_b16 v[186:187], v137 offset:8192
	ds_read_b64_tr_b16 v[188:189], v145 offset:8192
	s_waitcnt lgkmcnt(12)
	v_mfma_f32_16x16x32_bf16 v[110:113], v[220:223], v[194:197], v[110:113]
	s_waitcnt lgkmcnt(10)
	v_mfma_f32_16x16x32_bf16 v[90:93], v[220:223], v[90:93], v[172:175]
	s_waitcnt lgkmcnt(8)
	v_mfma_f32_16x16x32_bf16 v[82:85], v[220:223], v[82:85], v[176:179]
	s_waitcnt lgkmcnt(6)
	v_mfma_f32_16x16x32_bf16 v[86:89], v[220:223], v[86:89], v[182:185]
	s_waitcnt lgkmcnt(4)
	v_mfma_f32_16x16x32_bf16 v[94:97], v[220:223], v[94:97], v[120:123]
	s_waitcnt lgkmcnt(2)
	v_mfma_f32_16x16x32_bf16 v[102:105], v[220:223], v[190:193], v[102:105]
	s_waitcnt lgkmcnt(0)
	v_mfma_f32_16x16x32_bf16 v[98:101], v[220:223], v[186:189], v[98:101]
	s_cbranch_scc1 .LBB0_952
	v_mov_b32_e32 v159, v118
	v_mov_b32_e32 v160, v117
	s_branch .LBB0_928
